# no store-draining vmcnt(0) before the workgroup barrier that follows the NA units
# baseline (speedup 1.0000x reference)
.LBB0_526:
	v_readlane_b32 s0, v254, 63
	v_readlane_b32 s1, v255, 0
	v_readlane_b32 s4, v251, 4
	s_lshl_b64 s[0:1], s[0:1], 2
	v_readlane_b32 s18, v251, 18
	v_readlane_b32 s5, v251, 5
	v_readlane_b32 s19, v251, 19
	s_add_u32 s4, s18, s0
	s_addc_u32 s5, s19, s1
	v_readlane_b32 s8, v251, 8
	v_readlane_b32 s9, v251, 9
	s_add_u32 s4, s4, 0x2f700
	v_readlane_b32 s6, v251, 6
	s_addc_u32 s5, s5, 0
	v_readlane_b32 s8, v253, 62
	v_readlane_b32 s7, v251, 7
	s_add_u32 s6, s18, 0xb100000
	v_readlane_b32 s9, v253, 63
	s_addc_u32 s7, s19, 0
	s_andn2_b64 vcc, exec, s[8:9]
	v_readlane_b32 s10, v251, 10
	v_readlane_b32 s11, v251, 11
	v_readlane_b32 s12, v251, 12
	v_readlane_b32 s13, v251, 13
	v_readlane_b32 s14, v251, 14
	v_readlane_b32 s15, v251, 15
	v_readlane_b32 s16, v251, 16
	v_readlane_b32 s17, v251, 17
	s_barrier
	v_mbcnt_lo_u32_b32 v0, -1, 0
	v_mbcnt_hi_u32_b32 v0, -1, v0
	s_cbranch_vccnz .LBB0_559
	v_readlane_b32 s8, v254, 1
	v_readlane_b32 s9, v254, 2
	s_andn2_b64 vcc, exec, s[8:9]
	v_readlane_b32 s8, v254, 29
	s_cbranch_vccnz .LBB0_529
	v_readlane_b32 s8, v254, 3
